# plus conflict-free 4-bit XOR swizzle of the K tile in LDS for head-dim-128 attention (was 2-way bank conflict)
# speedup vs baseline: 1.0012x; 1.0012x over previous
; __device__ __forceinline__ int v_st(int k, int c) { const int kk = (k & ~0xC) | ((k & 4) << 1) | ((k & 8) >> 1); return ((kk >> 3) * 4 + (c >> 5)) * 512 + ((kk & 7) * 32 + (c & 31)) * 2; }
; __device__ __forceinline__ int v_rd_base(int lane) { return ((lane & 3) << 3) | (((lane >> 2) & 3) << 6) | (((lane >> 4) & 1) << 5) | (((lane >> 5) & 1) << 8); }
; #define SLOAD(i, k0) do { sr_[i].vs0 = *reinterpret_cast<const bf16x8*>(&Vh[(long)((k0) + sr) * LDP + sc]); sr_[i].vs1 = *reinterpret_cast<const bf16x8*>(&Vh[(long)((k0) + 32 + sr) * LDP + sc]); \
;     sr_[i].ks0 = *reinterpret_cast<const bf16x8*>(&Kh[(long)((k0) + ksr) * LDP + ksc]); if (DK == 128) sr_[i].ks1 = *reinterpret_cast<const bf16x8*>(&Kh[(long)((k0) + 32 + ksr) * LDP + ksc]); } while (0)
; template <int DK, bool NA, bool QL, int SD> ...
;     ...
;   const bf16* Qw = Qb + (long)(wid * 32 + r32) * LDP + hi * 8;
; #pragma unroll
;   for (int d0 = 0; d0 < DK / 16; ++d0) { const bf16x8 qv = *reinterpret_cast<const bf16x8*>(Qw + d0 * 16); if (QL) *reinterpret_cast<bf16x8*>(ql + d0 * 1024) = qv; else qr[d0] = qv; }
;   const int sr = tid >> 4, sc = (tid & 15) * 8, vst0 = v_st(sr, sc), vst1 = v_st(32 + sr, sc);
;   const int ksr = DK == 128 ? sr : (tid >> 3), ksc = DK == 128 ? sc : (tid & 7) * 8;
;   const int vb0 = (int)(uintptr_t)V_lds + v_rd_base(lane);
;   struct { bf16x8 vs0, vs1, ks0, ks1; } sr_[SD];
;     ...
;   f32x16 pA0, pA1, pB0, pB1; float mnA, mnB, alA, alB; bf16x8 pa0, pa1, pa2, pa3;
;   constexpr int SE = 0, SO = SD - 1;
;   SLOAD(SE, 0); asm volatile("s_waitcnt vmcnt(0)" ::: "memory"); SWRITE(0, SE); __syncthreads();
.LBB0_382:
	s_or_b64 exec, exec, s[0:1]
	v_mov_b32_e32 v36, v188
	v_readlane_b32 s0, v254, 57
	v_ashrrev_i32_e32 v0, 6, v36
	v_and_b32_e32 v38, 63, v36
	v_lshl_add_u32 v2, v0, 13, s0
	v_readlane_b32 s0, v253, 0
	v_and_b32_e32 v37, 31, v36
	v_lshlrev_b32_e32 v42, 4, v38
	v_readlane_b32 s1, v253, 1
	v_bfe_u32 v34, v36, 5, 1
	v_add_u32_e32 v147, v2, v42
	v_lshl_or_b32 v0, v0, 5, v37
	v_mov_b64_e32 v[2:3], s[0:1]
	s_movk_i32 s0, 0x2800
	v_mad_i64_i32 v[2:3], s[0:1], v0, s0, v[2:3]
	v_lshlrev_b32_e32 v0, 4, v34
	v_lshl_add_u64 v[6:7], v[2:3], 0, v[0:1]
	global_load_dwordx4 v[2:5], v[6:7], off
	global_load_dwordx4 v[44:47], v[6:7], off offset:32
	global_load_dwordx4 v[48:51], v[6:7], off offset:64
	global_load_dwordx4 v[52:55], v[6:7], off offset:96
	global_load_dwordx4 v[56:59], v[6:7], off offset:128
	global_load_dwordx4 v[60:63], v[6:7], off offset:160
	global_load_dwordx4 v[64:67], v[6:7], off offset:192
	global_load_dwordx4 v[68:71], v[6:7], off offset:224
	v_ashrrev_i32_e32 v39, 4, v36
	v_add_u32_e32 v20, 32, v39
	s_movk_i32 s4, 0x1400
	v_readlane_b32 s2, v253, 4
	v_readlane_b32 s3, v253, 5
	v_lshlrev_b32_e32 v35, 8, v37
	v_or_b32_e32 v43, 32, v0
	v_lshlrev_b32_e32 v6, 1, v20
	s_waitcnt vmcnt(7)
	ds_write_b128 v147, v[2:5]
	s_waitcnt vmcnt(6)
	ds_write_b128 v147, v[44:47] offset:1024
	s_waitcnt vmcnt(5)
	ds_write_b128 v147, v[48:51] offset:2048
	s_waitcnt vmcnt(4)
	ds_write_b128 v147, v[52:55] offset:3072
	s_waitcnt vmcnt(3)
	ds_write_b128 v147, v[56:59] offset:4096
	s_waitcnt vmcnt(2)
	ds_write_b128 v147, v[60:63] offset:5120
	s_waitcnt vmcnt(1)
	ds_write_b128 v147, v[64:67] offset:6144
	s_waitcnt vmcnt(0)
	ds_write_b128 v147, v[68:71] offset:7168
	v_and_b32_e32 v3, 0xfffff0, v39
	v_lshlrev_b32_e32 v4, 1, v39
	v_lshlrev_b32_e32 v2, 3, v36
	v_and_or_b32 v3, v4, 8, v3
	v_and_b32_e32 v40, 0x78, v2
	v_lshrrev_b32_e32 v4, 1, v39
	v_lshrrev_b32_e32 v3, 1, v3
	v_bfe_u32 v2, v2, 5, 2
	v_and_b32_e32 v5, 3, v39
	v_or_b32_e32 v3, v3, v2
	v_and_or_b32 v4, v4, 4, v5
	v_lshlrev_b32_e32 v18, 1, v40
	v_lshlrev_b32_e32 v3, 9, v3
	v_lshlrev_b32_e32 v4, 6, v4
	v_and_b32_e32 v5, 48, v18
	v_or3_b32 v19, v3, v4, v5
	v_and_b32_e32 v3, 0xfffff0, v20
	v_and_or_b32 v3, v6, 8, v3
	v_lshrrev_b32_e32 v3, 1, v3
	v_or_b32_e32 v2, v3, v2
	v_lshlrev_b32_e32 v2, 9, v2
	v_or3_b32 v21, v2, v4, v5
	v_mad_i64_i32 v[2:3], s[0:1], v39, s4, 0
	v_or_b32_e32 v2, v2, v40
	v_lshlrev_b64 v[10:11], 1, v[2:3]
	v_lshl_add_u64 v[2:3], s[2:3], 0, v[10:11]
	global_load_dwordx4 v[2:5], v[2:3], off
	v_mad_i64_i32 v[6:7], s[0:1], v20, s4, 0
	v_or_b32_e32 v6, v6, v40
	v_lshlrev_b64 v[14:15], 1, v[6:7]
	v_lshl_add_u64 v[6:7], s[2:3], 0, v[14:15]
	v_readlane_b32 s0, v253, 2
	global_load_dwordx4 v[6:9], v[6:7], off
	v_readlane_b32 s1, v253, 3
	v_add_u32_e32 v152, 0, v19
	v_add_u32_e32 v153, 0, v21
	v_lshl_add_u64 v[10:11], s[0:1], 0, v[10:11]
	v_lshl_add_u64 v[14:15], s[0:1], 0, v[14:15]
	global_load_dwordx4 v[10:13], v[10:11], off
	v_readlane_b32 s0, v255, 28
	global_load_dwordx4 v[14:17], v[14:15], off
	s_waitcnt vmcnt(0)
	v_readlane_b32 s1, v255, 29
	s_waitcnt vmcnt(3)
	ds_write_b128 v152, v[2:5]
	v_lshlrev_b32_e32 v2, 8, v39
	v_and_b32_e32 v3, 0xf0, v36
	v_bitop3_b32 v2, v18, v2, v3 bitop3:0xde
	v_add_u32_e32 v156, 0, v2
	v_lshlrev_b32_e32 v2, 8, v20
	v_bitop3_b32 v2, v18, v2, v3 bitop3:0xde
	v_add_u32_e32 v157, 0, v2
	v_lshlrev_b32_e32 v2, 4, v36
	v_and_b32_e32 v41, 0xf0, v2
	s_waitcnt vmcnt(2)
	ds_write_b128 v153, v[6:9]
	v_bitop3_b32 v6, v0, v35, v41 bitop3:0xde
	v_add_u32_e32 v158, 0, v6
	s_waitcnt vmcnt(1)
	ds_write_b128 v156, v[10:13] offset:32768
	v_bitop3_b32 v43, v43, v35, v41 bitop3:0xde
	s_waitcnt vmcnt(0)
	ds_write_b128 v157, v[14:17] offset:32768
	s_waitcnt lgkmcnt(0)
	s_barrier
; __device__ __forceinline__ int crow(int r, int hi) { return (r & 3) + 8 * (r >> 2) + 4 * hi; }
; template <int DK, bool QL>
; __device__ __forceinline__ void qkt(f32x16& p0, f32x16& p1, const bf16* Ks, const bf16x8* qr, const char* ql, int r32, int hi) {
;   p0 = f32x16{}; p1 = f32x16{};
; #pragma unroll
;   for (int d0 = 0; d0 < DK / 16; ++d0) { int cb = (d0 * 16 + hi * 8) * 2;
;     const bf16x8 qv = QL ? *reinterpret_cast<const bf16x8*>(ql + d0 * 1024) : qr[d0];
;     bf16x8 b0 = *reinterpret_cast<const bf16x8*>((const char*)Ks + kswz<DK>(r32, cb));
;     bf16x8 b1 = *reinterpret_cast<const bf16x8*>((const char*)Ks + kswz<DK>(32 + r32, cb));
;     p0 = __builtin_amdgcn_mfma_f32_32x32x16_bf16(b0, qv, p0, 0, 0, 0);
;     p1 = __builtin_amdgcn_mfma_f32_32x32x16_bf16(b1, qv, p1, 0, 0, 0); }
; }
; __device__ __forceinline__ void na_hook(f32x16& p0, f32x16& p1, int kr, int q_row, int q_col, int win_r, int win_c, const float* rpb, float inv_scale, int hi) {
;   const bool rowok = (kr >= win_r) && (kr < win_r + 8);
;   int ir = kr - q_row + 7; ir = ir < 0 ? 0 : (ir > 14 ? 14 : ir);
;   const float* rp = rpb + ir * 31;
; #pragma unroll
;   for (int r = 0; r < 16; ++r) {
;     const int kc = crow(r, hi);
;     { const bool ok = rowok && kc >= win_c && kc < win_c + 16; int ic = kc - q_col + 15; ic = ic < 0 ? 0 : (ic > 30 ? 30 : ic);
;       p0[r] = ok ? fmaf(rp[ic], inv_scale, p0[r]) : -1e30f; }
	ds_read_b128 v[2:5], v147
	ds_read_b128 v[6:9], v158 offset:32768
	ds_read_b128 v[10:13], v158 offset:40960
	s_waitcnt lgkmcnt(1)
	v_mfma_f32_32x32x16_bf16 v[18:33], v[6:9], v[2:5], 0
	v_add_u32_e32 v159, 0, v43
	ds_read_b128 v[44:47], v147 offset:1024
	ds_read_b128 v[48:51], v159 offset:32768
	ds_read_b128 v[52:55], v159 offset:40960
	v_or_b32_e32 v43, 64, v0
	v_bitop3_b32 v43, v43, v35, v41 bitop3:0xde
	v_add_u32_e32 v160, 0, v43
	v_or_b32_e32 v43, 0x60, v0
	s_waitcnt lgkmcnt(3)
	v_mfma_f32_32x32x16_bf16 v[2:17], v[10:13], v[2:5], 0
	v_bitop3_b32 v43, v43, v35, v41 bitop3:0xde
	v_add_u32_e32 v161, 0, v43
	v_or_b32_e32 v43, 0x80, v0
	v_bitop3_b32 v43, v43, v35, v41 bitop3:0xde
	v_add_u32_e32 v176, 0, v43
	v_or_b32_e32 v43, 0xa0, v0
	v_bitop3_b32 v43, v43, v35, v41 bitop3:0xde
	s_waitcnt lgkmcnt(1)
	v_mfma_f32_32x32x16_bf16 v[18:33], v[48:51], v[44:47], v[18:33]
	v_add_u32_e32 v177, 0, v43
	v_or_b32_e32 v43, 0xc0, v0
	v_bitop3_b32 v43, v43, v35, v41 bitop3:0xde
	v_add_u32_e32 v207, 0, v43
	v_or_b32_e32 v0, 0xe0, v0
	v_bitop3_b32 v0, v0, v35, v41 bitop3:0xde
	v_add_u32_e32 v208, 0, v0
	s_waitcnt lgkmcnt(0)
	v_mfma_f32_32x32x16_bf16 v[2:17], v[52:55], v[44:47], v[2:17]
	ds_read_b128 v[44:47], v147 offset:2048
	ds_read_b128 v[48:51], v160 offset:32768
	ds_read_b128 v[52:55], v160 offset:40960
	v_lshlrev_b32_e32 v0, 2, v34
	v_cmp_lt_u32_e64 s[2:3], v0, v182
	v_mov_b32_e32 v34, 0xf149f2ca
	v_sub_u32_e32 v41, v0, v181
	v_writelane_b32 v255, s2, 50
	s_waitcnt lgkmcnt(1)
	v_mfma_f32_32x32x16_bf16 v[18:33], v[48:51], v[44:47], v[18:33]
	v_mov_b32_e32 v43, 0xf149f2ca
	v_writelane_b32 v255, s3, 51
	s_nor_b64 s[2:3], s[0:1], s[2:3]
	s_waitcnt lgkmcnt(0)
	v_mfma_f32_32x32x16_bf16 v[2:17], v[52:55], v[44:47], v[2:17]
	ds_read_b128 v[44:47], v147 offset:3072
	ds_read_b128 v[48:51], v161 offset:32768
	ds_read_b128 v[52:55], v161 offset:40960
	s_waitcnt lgkmcnt(1)
	v_mfma_f32_32x32x16_bf16 v[18:33], v[48:51], v[44:47], v[18:33]
	s_waitcnt lgkmcnt(0)
	v_mfma_f32_32x32x16_bf16 v[2:17], v[52:55], v[44:47], v[2:17]
	ds_read_b128 v[44:47], v147 offset:4096
	ds_read_b128 v[48:51], v176 offset:32768
	ds_read_b128 v[52:55], v176 offset:40960
	s_waitcnt lgkmcnt(1)
	v_mfma_f32_32x32x16_bf16 v[18:33], v[48:51], v[44:47], v[18:33]
	s_waitcnt lgkmcnt(0)
	v_mfma_f32_32x32x16_bf16 v[2:17], v[52:55], v[44:47], v[2:17]
	ds_read_b128 v[44:47], v147 offset:5120
	ds_read_b128 v[48:51], v177 offset:32768
	ds_read_b128 v[52:55], v177 offset:40960
	s_waitcnt lgkmcnt(1)
	v_mfma_f32_32x32x16_bf16 v[18:33], v[48:51], v[44:47], v[18:33]
	s_waitcnt lgkmcnt(0)
	v_mfma_f32_32x32x16_bf16 v[2:17], v[52:55], v[44:47], v[2:17]
	ds_read_b128 v[44:47], v147 offset:6144
	ds_read_b128 v[48:51], v207 offset:32768
	ds_read_b128 v[52:55], v207 offset:40960
	s_waitcnt lgkmcnt(1)
	v_mfma_f32_32x32x16_bf16 v[18:33], v[48:51], v[44:47], v[18:33]
	s_waitcnt lgkmcnt(0)
	v_mfma_f32_32x32x16_bf16 v[2:17], v[52:55], v[44:47], v[2:17]
	ds_read_b128 v[44:47], v147 offset:7168
	ds_read_b128 v[48:51], v208 offset:32768
	ds_read_b128 v[52:55], v208 offset:40960
	s_waitcnt lgkmcnt(1)
	v_mfma_f32_32x32x16_bf16 v[18:33], v[48:51], v[44:47], v[18:33]
	s_waitcnt lgkmcnt(0)
	v_mfma_f32_32x32x16_bf16 v[2:17], v[52:55], v[44:47], v[2:17]
	s_and_saveexec_b64 s[0:1], s[2:3]
	s_cbranch_execz .LBB0_384
	v_sub_u32_e32 v35, v0, v181
	v_max_i32_e32 v35, -15, v35
	v_lshl_add_u32 v35, v35, 2, v183
	ds_read_b32 v35, v35 offset:928
	s_waitcnt lgkmcnt(0)
	s_nop 2
	v_fmamk_f32 v43, v35, 0x413504f3, v18

; __device__ __forceinline__ int v_st(int k, int c) { const int kk = (k & ~0xC) | ((k & 4) << 1) | ((k & 8) >> 1); return ((kk >> 3) * 4 + (c >> 5)) * 512 + ((kk & 7) * 32 + (c & 31)) * 2; }
; __device__ __forceinline__ int v_rd_base(int lane) { return ((lane & 3) << 3) | (((lane >> 2) & 3) << 6) | (((lane >> 4) & 1) << 5) | (((lane >> 5) & 1) << 8); }
; #define SLOAD(i, k0) do { sr_[i].vs0 = *reinterpret_cast<const bf16x8*>(&Vh[(long)((k0) + sr) * LDP + sc]); sr_[i].vs1 = *reinterpret_cast<const bf16x8*>(&Vh[(long)((k0) + 32 + sr) * LDP + sc]); \
;     sr_[i].ks0 = *reinterpret_cast<const bf16x8*>(&Kh[(long)((k0) + ksr) * LDP + ksc]); if (DK == 128) sr_[i].ks1 = *reinterpret_cast<const bf16x8*>(&Kh[(long)((k0) + 32 + ksr) * LDP + ksc]); } while (0)
; #define SWAIT() do { if (SD == 1) asm volatile("s_waitcnt vmcnt(0)" ::: "memory"); else if (DK == 128) asm volatile("s_waitcnt vmcnt(4)" ::: "memory"); else asm volatile("s_waitcnt vmcnt(3)" ::: "memory"); } while (0)
; #define HOOK(P0, P1, j) do { if (NA) na_hook(P0, P1, krow0 + (j), q_row, q_col, win_r, win_c, rpb, inv_scale, hi); } while (0)
; template <int DK, bool NA, bool QL, int SD> ...
;     ...
;   const bf16* Qw = Qb + (long)(wid * 32 + r32) * LDP + hi * 8;
; #pragma unroll
;   for (int d0 = 0; d0 < DK / 16; ++d0) { const bf16x8 qv = *reinterpret_cast<const bf16x8*>(Qw + d0 * 16); if (QL) *reinterpret_cast<bf16x8*>(ql + d0 * 1024) = qv; else qr[d0] = qv; }
;   const int sr = tid >> 4, sc = (tid & 15) * 8, vst0 = v_st(sr, sc), vst1 = v_st(32 + sr, sc);
;   const int ksr = DK == 128 ? sr : (tid >> 3), ksc = DK == 128 ? sc : (tid & 7) * 8;
;   const int vb0 = (int)(uintptr_t)V_lds + v_rd_base(lane);
;   struct { bf16x8 vs0, vs1, ks0, ks1; } sr_[SD];
;     ...
;   f32x16 pA0, pA1, pB0, pB1; float mnA, mnB, alA, alB; bf16x8 pa0, pa1, pa2, pa3;
;   constexpr int SE = 0, SO = SD - 1;
;   SLOAD(SE, 0); asm volatile("s_waitcnt vmcnt(0)" ::: "memory"); SWRITE(0, SE); __syncthreads();
;   qkt<DK, QL>(pA0, pA1, K_lds, qr, ql, r32, hi); HOOK(pA0, pA1, 0); partialSM(pA0, pA1, m_reg, mnA, alA, C, thrRaw);
;   SLOAD(SO, KVBLK); if (SD == 2) { if (2 < NT) SLOAD(SE, 2 * KVBLK); }
;   SWAIT(); SWRITE(1, SO); __syncthreads();
.LBB0_658:
	s_and_b64 vcc, exec, s[0:1]
	s_cbranch_vccz .LBB0_679
	v_mov_b32_e32 v50, v188
	v_readlane_b32 s0, v253, 11
	v_readlane_b32 s1, v253, 12
	v_ashrrev_i32_e32 v53, 6, v50
	v_and_b32_e32 v51, 31, v50
	v_lshl_or_b32 v0, v53, 5, v51
	v_mov_b64_e32 v[2:3], s[0:1]
	s_movk_i32 s3, 0x2800
	v_mad_i64_i32 v[2:3], s[0:1], v0, s3, v[2:3]
	v_lshrrev_b32_e32 v0, 1, v50
	v_and_b32_e32 v0, 16, v0
	v_ashrrev_i32_e32 v52, 4, v50
	v_lshl_add_u64 v[30:31], v[2:3], 0, v[0:1]
	v_lshlrev_b32_e32 v54, 3, v50
	v_add_u32_e32 v55, 32, v52
	s_movk_i32 s9, 0x1400
	global_load_dwordx4 v[2:5], v[30:31], off
	global_load_dwordx4 v[6:9], v[30:31], off offset:32
	global_load_dwordx4 v[10:13], v[30:31], off offset:64
	global_load_dwordx4 v[14:17], v[30:31], off offset:96
	global_load_dwordx4 v[18:21], v[30:31], off offset:128
	global_load_dwordx4 v[22:25], v[30:31], off offset:160
	global_load_dwordx4 v[26:29], v[30:31], off offset:192
	s_nop 0
	global_load_dwordx4 v[30:33], v[30:31], off offset:224
	v_and_b32_e32 v71, 0x78, v54
	v_mad_i64_i32 v[34:35], s[0:1], v52, s9, 0
	v_mad_i64_i32 v[36:37], s[0:1], v55, s9, 0
	v_or_b32_e32 v34, v34, v71
	v_readlane_b32 s6, v253, 15
	v_or_b32_e32 v36, v36, v71
	v_readlane_b32 s4, v253, 13
	v_lshlrev_b64 v[42:43], 1, v[34:35]
	v_readlane_b32 s7, v253, 16
	v_lshlrev_b64 v[44:45], 1, v[36:37]
	v_readlane_b32 s5, v253, 14
	v_lshl_add_u64 v[34:35], s[6:7], 0, v[42:43]
	v_lshl_add_u64 v[38:39], s[6:7], 0, v[44:45]
	v_lshl_add_u64 v[42:43], s[4:5], 0, v[42:43]
	v_lshl_add_u64 v[46:47], s[4:5], 0, v[44:45]
	global_load_dwordx4 v[34:37], v[34:35], off
	s_nop 0
	global_load_dwordx4 v[38:41], v[38:39], off
	s_nop 0
	global_load_dwordx4 v[42:45], v[42:43], off
	s_nop 0
	global_load_dwordx4 v[46:49], v[46:47], off
	v_and_b32_e32 v72, 63, v50
	v_readlane_b32 s0, v254, 57
	v_lshlrev_b32_e32 v57, 4, v72
	v_and_b32_e32 v58, 0xfffff0, v52
	v_lshl_add_u32 v53, v53, 13, s0
	v_lshlrev_b32_e32 v59, 1, v52
	v_lshrrev_b32_e32 v60, 1, v52
	v_and_b32_e32 v61, 3, v52
	v_add_u32_e32 v153, v53, v57
	v_and_or_b32 v53, v59, 8, v58
	v_and_or_b32 v58, v60, 4, v61
	v_and_b32_e32 v60, 0xfffff0, v55
	v_lshlrev_b32_e32 v61, 1, v55
	v_and_b32_e32 v56, 0xf0, v50
	v_bfe_u32 v54, v54, 5, 2
	v_lshlrev_b32_e32 v62, 8, v52
	v_lshlrev_b32_e32 v59, 1, v71
	v_lshlrev_b32_e32 v55, 8, v55
	v_lshrrev_b32_e32 v53, 1, v53
	v_and_or_b32 v60, v61, 8, v60
	v_bitop3_b32 v61, v59, v62, v56 bitop3:0xde
	v_bitop3_b32 v55, v59, v55, v56 bitop3:0xde
	v_or_b32_e32 v53, v53, v54
	v_lshrrev_b32_e32 v56, 1, v60
	v_lshlrev_b32_e32 v58, 6, v58
	v_and_b32_e32 v63, 48, v59
	v_lshlrev_b32_e32 v53, 9, v53
	v_or_b32_e32 v54, v56, v54
	v_or3_b32 v53, v53, v58, v63
	v_lshlrev_b32_e32 v54, 9, v54
	v_or3_b32 v54, v54, v58, v63
	v_add_u32_e32 v209, 0, v53
	v_lshlrev_b32_e32 v53, 8, v51
	v_add_u32_e32 v177, 0, v61
	v_add_u32_e32 v208, 0, v55
	v_add_u32_e32 v210, 0, v54
	v_and_b32_e32 v54, 0x3fffffc0, v50
	s_add_i32 s0, 0, 0x10000
	v_lshl_add_u32 v148, v54, 2, s0
	v_readlane_b32 s12, v254, 62
	s_cmp_lg_u32 0, -1
	v_readlane_b32 s13, v254, 63
	v_readlane_b32 s14, v255, 0
	v_readlane_b32 s15, v255, 1
	s_mov_b32 s8, -1
	s_cselect_b32 s2, 0, 0
	v_readlane_b32 s16, v255, 2
	v_readlane_b32 s17, v255, 3
	s_waitcnt vmcnt(11)
	ds_write_b128 v153, v[2:5]
	s_waitcnt vmcnt(10)
	ds_write_b128 v153, v[6:9] offset:1024
	s_waitcnt vmcnt(9)
	ds_write_b128 v153, v[10:13] offset:2048
	s_waitcnt vmcnt(8)
	ds_write_b128 v153, v[14:17] offset:3072
	s_waitcnt vmcnt(7)
	ds_write_b128 v153, v[18:21] offset:4096
	s_waitcnt vmcnt(6)
	ds_write_b128 v153, v[22:25] offset:5120
	s_waitcnt vmcnt(5)
	ds_write_b128 v153, v[26:29] offset:6144
	s_waitcnt vmcnt(4)
	ds_write_b128 v153, v[30:33] offset:7168
	v_lshlrev_b32_e32 v2, 4, v50
	v_and_b32_e32 v58, 0xf0, v2
	v_bitop3_b32 v2, v0, v53, v58 bitop3:0xde
	v_add_u32_e32 v159, 0, v2
	s_waitcnt vmcnt(0)
	s_waitcnt vmcnt(3)
	ds_write_b128 v209, v[34:37]
	s_waitcnt vmcnt(2)
	ds_write_b128 v210, v[38:41]
	s_waitcnt vmcnt(1)
	ds_write_b128 v177, v[42:45] offset:32768
	s_waitcnt vmcnt(0)
	ds_write_b128 v208, v[46:49] offset:32768
	s_waitcnt lgkmcnt(0)
	s_barrier
	ds_read_b128 v[2:5], v159 offset:32768
	ds_read_b128 v[6:9], v153
	ds_read_b128 v[10:13], v159 offset:40960
	ds_read_b128 v[14:17], v153 offset:1024
	s_waitcnt lgkmcnt(2)
	v_mfma_f32_32x32x16_bf16 v[34:49], v[2:5], v[6:9], 0
	v_or_b32_e32 v2, 32, v0
	v_bitop3_b32 v2, v2, v53, v58 bitop3:0xde
	v_add_u32_e32 v207, 0, v2
	v_readlane_b32 s18, v255, 4
	v_readlane_b32 s19, v255, 5
	v_readlane_b32 s20, v255, 6
	v_readlane_b32 s21, v255, 7
	s_waitcnt lgkmcnt(1)
	v_mfma_f32_32x32x16_bf16 v[18:33], v[10:13], v[6:9], 0
	ds_read_b128 v[2:5], v207 offset:32768
	ds_read_b128 v[6:9], v207 offset:40960
	v_readlane_b32 s22, v255, 8
	v_readlane_b32 s23, v255, 9
	v_readlane_b32 s24, v255, 10
	v_readlane_b32 s25, v255, 11
	v_readlane_b32 s26, v255, 12
	v_readlane_b32 s27, v255, 13
	s_waitcnt lgkmcnt(1)
	v_mfma_f32_32x32x16_bf16 v[34:49], v[2:5], v[14:17], v[34:49]
	v_or_b32_e32 v2, 64, v0
	v_bitop3_b32 v2, v2, v53, v58 bitop3:0xde
	v_add_u32_e32 v161, 0, v2
	s_mov_b32 s12, s13
	s_mov_b32 s14, s13
	s_mov_b32 s15, s13
	s_mov_b32 s1, s13
	s_waitcnt lgkmcnt(0)
	v_mfma_f32_32x32x16_bf16 v[18:33], v[6:9], v[14:17], v[18:33]
	ds_read_b128 v[2:5], v161 offset:32768
	ds_read_b128 v[6:9], v153 offset:2048
	ds_read_b128 v[10:13], v161 offset:40960
	ds_read_b128 v[14:17], v153 offset:3072
	s_mov_b32 s16, s13
	s_mov_b32 s17, s13
	s_mov_b32 s18, s13
	s_mov_b32 s19, s13
	s_mov_b32 s20, s13
	s_mov_b32 s21, s13
	s_waitcnt lgkmcnt(2)
	v_mfma_f32_32x32x16_bf16 v[34:49], v[2:5], v[6:9], v[34:49]
	v_or_b32_e32 v2, 0x60, v0
	v_bitop3_b32 v2, v2, v53, v58 bitop3:0xde
	v_add_u32_e32 v160, 0, v2
	s_mov_b32 s22, s13
	s_mov_b32 s23, s13
	s_mov_b32 s24, s13
	s_mov_b32 s25, s13
	s_waitcnt lgkmcnt(1)
; __device__ __forceinline__ int v_rd_base(int lane) { return ((lane & 3) << 3) | (((lane >> 2) & 3) << 6) | (((lane >> 4) & 1) << 5) | (((lane >> 5) & 1) << 8); }
; template <int DK, bool QL>
; __device__ __forceinline__ void qkt(f32x16& p0, f32x16& p1, const bf16* Ks, const bf16x8* qr, const char* ql, int r32, int hi) {
;   p0 = f32x16{}; p1 = f32x16{};
; #pragma unroll
;   for (int d0 = 0; d0 < DK / 16; ++d0) { int cb = (d0 * 16 + hi * 8) * 2;
;     const bf16x8 qv = QL ? *reinterpret_cast<const bf16x8*>(ql + d0 * 1024) : qr[d0];
;     bf16x8 b0 = *reinterpret_cast<const bf16x8*>((const char*)Ks + kswz<DK>(r32, cb));
;     bf16x8 b1 = *reinterpret_cast<const bf16x8*>((const char*)Ks + kswz<DK>(32 + r32, cb));
;     p0 = __builtin_amdgcn_mfma_f32_32x32x16_bf16(b0, qv, p0, 0, 0, 0);
;     p1 = __builtin_amdgcn_mfma_f32_32x32x16_bf16(b1, qv, p1, 0, 0, 0); }
; template <int DK, bool NA, bool QL, int SD> ...
;     ...
;   const int vb0 = (int)(uintptr_t)V_lds + v_rd_base(lane);
	v_mfma_f32_32x32x16_bf16 v[18:33], v[10:13], v[6:9], v[18:33]
	ds_read_b128 v[2:5], v160 offset:32768
	ds_read_b128 v[6:9], v160 offset:40960
	s_mov_b32 s26, s13
	s_mov_b32 s27, s13
	v_mov_b32_e32 v150, 0
	v_lshl_add_u32 v149, v51, 2, v148
	v_mov_b32_e32 v51, v150
	s_waitcnt lgkmcnt(1)
	v_mfma_f32_32x32x16_bf16 v[34:49], v[2:5], v[14:17], v[34:49]
	v_or_b32_e32 v2, 0x80, v0
	v_bitop3_b32 v2, v2, v53, v58 bitop3:0xde
	v_add_u32_e32 v158, 0, v2
	s_waitcnt lgkmcnt(0)
	v_mfma_f32_32x32x16_bf16 v[18:33], v[6:9], v[14:17], v[18:33]
	ds_read_b128 v[2:5], v158 offset:32768
	ds_read_b128 v[6:9], v153 offset:4096
	ds_read_b128 v[10:13], v158 offset:40960
	ds_read_b128 v[14:17], v153 offset:5120
	s_waitcnt lgkmcnt(2)
	v_mfma_f32_32x32x16_bf16 v[34:49], v[2:5], v[6:9], v[34:49]
	v_or_b32_e32 v2, 0xa0, v0
	v_bitop3_b32 v2, v2, v53, v58 bitop3:0xde
	v_add_u32_e32 v156, 0, v2
	ds_read_b128 v[2:5], v156 offset:32768
	s_waitcnt lgkmcnt(2)
	v_mfma_f32_32x32x16_bf16 v[18:33], v[10:13], v[6:9], v[18:33]
	v_lshlrev_b32_e32 v10, 3, v72
	v_and_b32_e32 v6, 0xc0, v57
	v_and_or_b32 v11, v10, 24, v6
	ds_read_b128 v[6:9], v156 offset:40960
	v_lshlrev_b32_e32 v12, 1, v50
	s_waitcnt lgkmcnt(0)
	v_mfma_f32_32x32x16_bf16 v[18:33], v[6:9], v[14:17], v[18:33]
	ds_read_b128 v[6:9], v153 offset:6144
	v_mfma_f32_32x32x16_bf16 v[34:49], v[2:5], v[14:17], v[34:49]
	v_and_b32_e32 v2, 32, v12
	v_and_b32_e32 v3, 0x100, v10
	v_or3_b32 v73, v11, v2, v3
	v_or_b32_e32 v2, 0xc0, v0
	v_bitop3_b32 v2, v2, v53, v58 bitop3:0xde
	v_add_u32_e32 v157, 0, v2
	ds_read_b128 v[2:5], v157 offset:32768
	s_waitcnt lgkmcnt(0)
	v_mfma_f32_32x32x16_bf16 v[34:49], v[2:5], v[6:9], v[34:49]
	v_or_b32_e32 v2, 0xe0, v0
	v_bitop3_b32 v2, v2, v53, v58 bitop3:0xde
	v_add_u32_e32 v176, 0, v2
	ds_read_b128 v[10:13], v157 offset:40960
	ds_read_b128 v[54:57], v153 offset:7168
	ds_read_b128 v[2:5], v176 offset:32768
	ds_read_b128 v[58:61], v176 offset:40960
	v_add_u32_e32 v152, s2, v73
	s_waitcnt lgkmcnt(3)
	v_mfma_f32_32x32x16_bf16 v[18:33], v[10:13], v[6:9], v[18:33]
	v_writelane_b32 v254, s0, 62
	s_nop 1
	v_writelane_b32 v255, s2, 0
	v_writelane_b32 v255, s3, 1
	v_writelane_b32 v255, s4, 2
	v_writelane_b32 v255, s5, 3
	s_waitcnt lgkmcnt(1)
	v_mfma_f32_32x32x16_bf16 v[34:49], v[2:5], v[54:57], v[34:49]
	v_writelane_b32 v255, s6, 4
	v_writelane_b32 v255, s7, 5
	v_writelane_b32 v255, s8, 6
	v_writelane_b32 v255, s9, 7
	v_writelane_b32 v255, s10, 8
	v_writelane_b32 v255, s11, 9
	v_writelane_b32 v255, s12, 10
	s_waitcnt lgkmcnt(0)
; #define SLOAD(i, k0) do { sr_[i].vs0 = *reinterpret_cast<const bf16x8*>(&Vh[(long)((k0) + sr) * LDP + sc]); sr_[i].vs1 = *reinterpret_cast<const bf16x8*>(&Vh[(long)((k0) + 32 + sr) * LDP + sc]); \
;     sr_[i].ks0 = *reinterpret_cast<const bf16x8*>(&Kh[(long)((k0) + ksr) * LDP + ksc]); if (DK == 128) sr_[i].ks1 = *reinterpret_cast<const bf16x8*>(&Kh[(long)((k0) + 32 + ksr) * LDP + ksc]); } while (0)
; #define SWAIT() do { if (SD == 1) asm volatile("s_waitcnt vmcnt(0)" ::: "memory"); else if (DK == 128) asm volatile("s_waitcnt vmcnt(4)" ::: "memory"); else asm volatile("s_waitcnt vmcnt(3)" ::: "memory"); } while (0)
; #define HOOK(P0, P1, j) do { if (NA) na_hook(P0, P1, krow0 + (j), q_row, q_col, win_r, win_c, rpb, inv_scale, hi); } while (0)
; __device__ __forceinline__ void partialSM(f32x16& p0, f32x16& p1, float& m_reg, float& mn, float& alpha, float C, float thrRaw) {
;   float pmax = p0[0];
; #pragma unroll
;   for (int r = 1; r < 16; ++r) pmax = fmaxf(pmax, p0[r]);
; #pragma unroll
;   for (int r = 0; r < 16; ++r) pmax = fmaxf(pmax, p1[r]);
;   { auto rr = __builtin_amdgcn_permlane32_swap(__float_as_uint(pmax), __float_as_uint(pmax), false, false);
;     pmax = fmaxf(__uint_as_float(rr[0]), __uint_as_float(rr[1])); }
;   if (__builtin_expect(__all(pmax - m_reg <= thrRaw), 1)) { mn = m_reg; alpha = 1.f; }
;   else { mn = fmaxf(m_reg, pmax); alpha = __builtin_amdgcn_exp2f((m_reg - mn) * C); m_reg = mn; }
;   float mnC = -mn * C;
; #pragma unroll
;   for (int r = 0; r < 16; ++r) p0[r] = fmaf(p0[r], C, mnC);
; #pragma unroll
;   for (int r = 0; r < 16; ++r) p1[r] = fmaf(p1[r], C, mnC);
; #pragma unroll
;   for (int r = 0; r < 16; ++r) p0[r] = __builtin_amdgcn_exp2f(p0[r]);
; template <int DK, bool NA, bool QL, int SD> ...
;     ...
;   qkt<DK, QL>(pA0, pA1, K_lds, qr, ql, r32, hi); HOOK(pA0, pA1, 0); partialSM(pA0, pA1, m_reg, mnA, alA, C, thrRaw);
;   SLOAD(SO, KVBLK); if (SD == 2) { if (2 < NT) SLOAD(SE, 2 * KVBLK); }
;   SWAIT(); SWRITE(1, SO); __syncthreads();
	v_mfma_f32_32x32x16_bf16 v[18:33], v[58:61], v[54:57], v[18:33]
	s_nop 2
	v_max_f32_e32 v53, v35, v35
	v_max_f32_e32 v54, v34, v34
	v_max_f32_e32 v53, v54, v53
	v_max3_f32 v53, v53, v36, v37
	v_max3_f32 v53, v53, v38, v39
	v_max3_f32 v53, v53, v40, v41
	v_max3_f32 v53, v53, v42, v43
	v_max3_f32 v53, v53, v44, v45
	v_max3_f32 v53, v53, v46, v47
	v_max3_f32 v53, v53, v48, v49
	v_max3_f32 v53, v53, v18, v19
	v_max3_f32 v53, v53, v20, v21
	v_max3_f32 v53, v53, v22, v23
	v_max3_f32 v53, v53, v24, v25
	v_max3_f32 v53, v53, v26, v27
	v_max3_f32 v53, v53, v28, v29
	v_max3_f32 v53, v53, v30, v31
	v_max3_f32 v53, v53, v32, v33
	v_mov_b32_e32 v70, v53
	v_writelane_b32 v255, s13, 11
	s_nop 0
	v_permlane32_swap_b32_e32 v53, v70
	v_writelane_b32 v255, s14, 12
	v_add_u32_e32 v54, 64, v52
	v_add_u32_e32 v56, 0x60, v52
	v_max_f32_e32 v70, v70, v70
	v_max_f32_e32 v53, v53, v53
	v_writelane_b32 v254, s1, 63
	v_writelane_b32 v255, s15, 13
	v_mad_i64_i32 v[54:55], s[0:1], v54, s9, 0
	v_mad_i64_i32 v[56:57], s[0:1], v56, s9, 0
	v_max_f32_e32 v53, v53, v70
	v_add_f32_e32 v70, 0x7149f2ca, v53
	s_mov_b32 s0, 0x42b504f3
	v_max_f32_e32 v53, 0xf149f2ca, v53
	v_cmp_ge_f32_e32 vcc, s0, v70
	v_sub_f32_e32 v70, 0xf149f2ca, v53
	v_mul_f32_e32 v70, 0x3e0293ee, v70
	v_exp_f32_e32 v70, v70
	s_cmp_eq_u64 vcc, exec
	s_cselect_b64 vcc, -1, 0
	v_cndmask_b32_e32 v134, v53, v199, vcc
	v_cndmask_b32_e64 v211, v70, 1.0, vcc
	v_mul_f32_e32 v70, 0xbe0293ee, v134
	v_fmamk_f32 v53, v34, 0x3e0293ee, v70
	v_add_u32_e32 v34, 0xa0, v52
	v_or_b32_e32 v54, v54, v71
	v_or_b32_e32 v56, v56, v71
	v_fmamk_f32 v74, v35, 0x3e0293ee, v70
	v_fmamk_f32 v77, v38, 0x3e0293ee, v70
	v_mad_i64_i32 v[34:35], s[0:1], v34, s9, 0
	v_add_u32_e32 v38, 0x80, v52
	v_lshlrev_b64 v[62:63], 1, v[54:55]
	v_lshlrev_b64 v[64:65], 1, v[56:57]
	v_fmamk_f32 v78, v39, 0x3e0293ee, v70
	v_or_b32_e32 v34, v34, v71
	v_mad_i64_i32 v[38:39], s[0:1], v38, s9, 0
	v_lshl_add_u64 v[54:55], s[6:7], 0, v[62:63]
	v_lshl_add_u64 v[58:59], s[6:7], 0, v[64:65]
	v_lshl_add_u64 v[62:63], s[4:5], 0, v[62:63]
	v_lshl_add_u64 v[66:67], s[4:5], 0, v[64:65]
	v_lshlrev_b64 v[34:35], 1, v[34:35]
	v_or_b32_e32 v38, v38, v71
	global_load_dwordx4 v[54:57], v[54:55], off
	s_nop 0
	global_load_dwordx4 v[58:61], v[58:59], off
	s_nop 0
	global_load_dwordx4 v[62:65], v[62:63], off
	s_nop 0
	global_load_dwordx4 v[66:69], v[66:67], off
	v_fmamk_f32 v75, v36, 0x3e0293ee, v70
	v_fmamk_f32 v76, v37, 0x3e0293ee, v70
	v_lshl_add_u64 v[36:37], s[4:5], 0, v[34:35]
	v_lshlrev_b64 v[38:39], 1, v[38:39]
	v_lshl_add_u64 v[34:35], s[6:7], 0, v[34:35]
	v_fmamk_f32 v79, v40, 0x3e0293ee, v70
	v_fmamk_f32 v80, v41, 0x3e0293ee, v70
	v_lshl_add_u64 v[40:41], s[4:5], 0, v[38:39]
	global_load_dwordx4 v[102:105], v[36:37], off
	global_load_dwordx4 v[98:101], v[40:41], off
	v_lshl_add_u64 v[36:37], s[6:7], 0, v[38:39]
	global_load_dwordx4 v[110:113], v[34:35], off
	global_load_dwordx4 v[106:109], v[36:37], off
	v_mov_b32_e32 v36, v70
	s_mov_b32 s0, 0x3e0293ee
	s_addk_i32 s2, 0x4000
	v_fmamk_f32 v42, v42, 0x3e0293ee, v70
	v_fmamk_f32 v43, v43, 0x3e0293ee, v70
	v_fmamk_f32 v44, v44, 0x3e0293ee, v70
	v_fmamk_f32 v45, v45, 0x3e0293ee, v70
	v_fmamk_f32 v46, v46, 0x3e0293ee, v70
	v_fmamk_f32 v34, v47, 0x3e0293ee, v70
	v_fmamk_f32 v35, v48, 0x3e0293ee, v70
	v_fmac_f32_e32 v36, 0x3e0293ee, v49
	v_pk_fma_f32 v[126:127], v[18:19], s[0:1], v[70:71] op_sel_hi:[1,0,0]
	v_add_u32_e32 v151, s2, v73
	v_mad_i64_i32 v[18:19], s[2:3], v52, s3, 0
	v_mov_b64_e32 v[2:3], s[12:13]
	v_pk_fma_f32 v[124:125], v[20:21], s[0:1], v[70:71] op_sel_hi:[1,0,0]
	v_exp_f32_e32 v145, v53
	v_exp_f32_e32 v216, v74
	v_exp_f32_e32 v131, v75
	v_exp_f32_e32 v215, v76
	v_exp_f32_e32 v132, v77
	v_exp_f32_e32 v144, v78
	v_exp_f32_e32 v133, v79
	v_exp_f32_e32 v143, v80
	v_exp_f32_e32 v140, v42
	v_exp_f32_e32 v142, v43
	v_exp_f32_e32 v139, v44
	v_exp_f32_e32 v141, v45
	v_exp_f32_e32 v136, v46
	v_exp_f32_e32 v138, v34
	v_exp_f32_e32 v135, v35
	v_exp_f32_e32 v137, v36
	v_and_b32_e32 v20, 15, v50
	v_readlane_b32 s2, v254, 30
	v_mov_b64_e32 v[16:17], s[26:27]
	s_waitcnt vmcnt(4)
	v_lshl_or_b32 v18, v20, 4, v18
	v_readlane_b32 s3, v254, 31
	v_mov_b64_e32 v[4:5], s[14:15]
	v_mov_b64_e32 v[6:7], s[16:17]
	v_mov_b64_e32 v[8:9], s[18:19]
	v_mov_b64_e32 v[10:11], s[20:21]
	v_mov_b64_e32 v[12:13], s[22:23]
	v_mov_b64_e32 v[14:15], s[24:25]
	v_pk_fma_f32 v[120:121], v[32:33], s[0:1], v[70:71] op_sel_hi:[1,0,0]
	v_pk_fma_f32 v[122:123], v[30:31], s[0:1], v[70:71] op_sel_hi:[1,0,0]
	v_pk_fma_f32 v[128:129], v[28:29], s[0:1], v[70:71] op_sel_hi:[1,0,0]
	v_pk_fma_f32 v[114:115], v[26:27], s[0:1], v[70:71] op_sel_hi:[1,0,0]
	v_pk_fma_f32 v[116:117], v[24:25], s[0:1], v[70:71] op_sel_hi:[1,0,0]
	v_pk_fma_f32 v[118:119], v[22:23], s[0:1], v[70:71] op_sel_hi:[1,0,0]
	v_lshl_add_u64 v[146:147], s[2:3], 0, v[18:19]
	v_mov_b64_e32 v[32:33], v[16:17]
	s_waitcnt vmcnt(7)
	ds_write_b128 v209, v[54:57] offset:16384
	s_waitcnt vmcnt(6)
	ds_write_b128 v210, v[58:61] offset:16384
	s_waitcnt vmcnt(5)
	ds_write_b128 v177, v[62:65] offset:49152
	s_waitcnt vmcnt(4)
	ds_write_b128 v208, v[66:69] offset:49152
	v_cmp_gt_u32_e64 s[0:1], 32, v72
	v_mov_b64_e32 v[30:31], v[14:15]
	v_mov_b64_e32 v[28:29], v[12:13]
	v_mov_b64_e32 v[26:27], v[10:11]
	v_mov_b64_e32 v[24:25], v[8:9]
	v_mov_b64_e32 v[22:23], v[6:7]
	v_mov_b64_e32 v[20:21], v[4:5]
	v_mov_b64_e32 v[18:19], v[2:3]
	v_mov_b32_e32 v34, 0
	v_mov_b32_e32 v35, v150
	v_mov_b32_e32 v36, v150
	v_mov_b32_e32 v37, v150
	v_mov_b32_e32 v38, v150
	v_mov_b32_e32 v39, v150
	v_mov_b32_e32 v40, v150
	v_mov_b32_e32 v41, v150
	v_mov_b32_e32 v42, v150
	v_mov_b32_e32 v43, v150
	v_mov_b32_e32 v44, v150
	v_mov_b32_e32 v45, v150
	v_mov_b32_e32 v46, v150
	v_mov_b32_e32 v47, v150
	v_mov_b32_e32 v48, v150
	v_mov_b32_e32 v49, v150
	v_mov_b32_e32 v50, 0
	v_mov_b32_e32 v52, v150
	v_mov_b32_e32 v53, v150
	v_mov_b32_e32 v54, v150
	v_mov_b32_e32 v55, v150
	v_mov_b32_e32 v56, v150
	v_mov_b32_e32 v57, v150
	v_mov_b32_e32 v58, v150
	v_mov_b32_e32 v59, v150
	v_mov_b32_e32 v60, v150
	v_mov_b32_e32 v61, v150
	v_mov_b32_e32 v62, v150
	v_mov_b32_e32 v63, v150
	v_mov_b32_e32 v64, v150
	v_mov_b32_e32 v65, v150
	s_waitcnt lgkmcnt(0)
	s_barrier
